# final-norm loop software-pipelined two rows deep (exact vmcnt counts, store-data wait states)
# baseline (speedup 1.0000x reference)
; __device__ __forceinline__ float bf_lo(unsigned w) { return __uint_as_float(w << 16); }
; __device__ __forceinline__ float bf_hi(unsigned w) { return __uint_as_float(w & 0xffff0000u); }
; __device__ __forceinline__ float rs_to_r(float ss) { return __builtin_amdgcn_rsqf(ss * (1.0f / DM) + RMS_EPS); }
; __device__ __forceinline__ void final_norm_phase(const bf16_t* __restrict__ hb, const float* __restrict__ g, const float* __restrict__ rs, float* __restrict__ dst, int G, int bid) {
;     const int wave = threadIdx.x >> 6, lane = threadIdx.x & 63;
;     for (int row = bid * 8 + wave; row < SEQ; row += G * 8) {
;         const bf16_t* p = hb + (size_t)row * DM + lane * 8;
;         u32x4 v[4];
; #pragma unroll
;         for (int i = 0; i < 4; ++i) v[i] = *(const u32x4*)(p + i * 512);
;         const float r = rs_to_r(rs[row]);
;         float* q = dst + (size_t)row * DM + lane * 8;
; #pragma unroll
;         for (int i = 0; i < 4; ++i) {
;             const f32x4 g0 = *(const f32x4*)(g + i * 512 + lane * 8), g1 = *(const f32x4*)(g + i * 512 + lane * 8 + 4);
;             const f32x4 a = (f32x4){bf_lo(v[i].x), bf_hi(v[i].x), bf_lo(v[i].y), bf_hi(v[i].y)}, b = (f32x4){bf_lo(v[i].z), bf_hi(v[i].z), bf_lo(v[i].w), bf_hi(v[i].w)};
;             *(f32x4*)(q + i * 512) = a * r * g0; *(f32x4*)(q + i * 512 + 4) = b * r * g1;
;         }
;     }
; }
.LBB0_1635:
	s_cmp_lt_i32 s84, 19
	s_cselect_b64 s[2:3], -1, 0
	s_and_b64 s[0:1], s[2:3], s[0:1]
	s_andn2_b64 vcc, exec, s[0:1]
	s_cbranch_vccnz .LBB0_1639
	s_waitcnt vmcnt(2)
	v_lshrrev_b32_e32 v0, 6, v224
	v_lshl_add_u32 v32, s79, 3, v0
	s_movk_i32 s0, 0x4000
	v_cmp_gt_i32_e32 vcc, s0, v32
	s_and_saveexec_b64 s[0:1], vcc
	s_cbranch_execz .LBB0_1639
	v_readlane_b32 s0, v252, 0
	v_readlane_b32 s1, v252, 1
	s_load_dwordx2 s[0:1], s[0:1], 0x68
	v_lshlrev_b32_e32 v0, 5, v224
	v_mov_b32_e32 v25, 0
	v_and_b32_e32 v24, 0x7e0, v0
	s_mov_b64 s[6:7], 0x1000
	s_waitcnt lgkmcnt(0)
	v_lshl_add_u64 v[26:27], s[0:1], 0, v[24:25]
	v_add_co_u32_e32 v34, vcc, 0x1000, v26
	global_load_dwordx4 v[0:3], v24, s[0:1] offset:2064
	global_load_dwordx4 v[4:7], v24, s[0:1] offset:2048
	v_addc_co_u32_e32 v35, vcc, 0, v27, vcc
	v_lshl_add_u64 v[28:29], v[26:27], 0, s[6:7]
	global_load_dwordx4 v[8:11], v[34:35], off
	global_load_dwordx4 v[12:15], v[28:29], off offset:16
	global_load_dwordx4 v[16:19], v24, s[0:1] offset:16
	global_load_dwordx4 v[20:23], v24, s[0:1]
	s_mov_b64 s[0:1], 0x1800
	v_lshl_add_u64 v[36:37], v[26:27], 0, s[0:1]
	global_load_dwordx4 v[24:27], v[34:35], off offset:2048
	global_load_dwordx4 v[28:31], v[36:37], off offset:16
	v_ashrrev_i32_e32 v33, 31, v32
	v_and_b32_e32 v40, 63, v224
	v_lshlrev_b64 v[38:39], 13, v[32:33]
	s_lshl_b32 s0, s78, 3
	v_lshl_or_b32 v38, v40, 5, v38
	v_mov_b64_e32 v[34:35], 0x2a9e0000
	s_ashr_i32 s1, s0, 31
	v_lshlrev_b64 v[36:37], 12, v[32:33]
	v_lshl_add_u64 v[38:39], s[80:81], 0, v[38:39]
	v_lshl_add_u64 v[34:35], v[32:33], 2, v[34:35]
	s_lshl_b64 s[2:3], s[0:1], 2
	v_lshl_or_b32 v36, v40, 4, v36
	s_lshl_b64 s[4:5], s[0:1], 12
	v_lshl_add_u64 v[38:39], v[38:39], 0, s[6:7]
	s_lshl_b64 s[6:7], s[0:1], 13
	s_mov_b64 s[8:9], 0
	v_mov_b32_e32 v33, 0x358637bd
	s_movk_i32 s1, 0x3fff
	s_cmpk_eq_u32 s78, 0x100
	s_cbranch_scc0 .LBB0_1638
	s_mov_b32 s99, 3
	v_lshl_add_u64 v[42:43], s[82:83], 0, v[34:35]
	global_load_dword v58, v[42:43], off
	v_lshl_add_u64 v[40:41], s[82:83], 0, v[36:37]
	v_add_co_u32_e32 v56, vcc, 0x26980000, v40
	v_add_u32_e32 v32, s0, v32
	s_nop 0
	v_addc_co_u32_e32 v57, vcc, 0, v41, vcc
	global_load_dwordx4 v[40:43], v[56:57], off
	global_load_dwordx4 v[44:47], v[56:57], off offset:1024
	global_load_dwordx4 v[48:51], v[56:57], off offset:2048
	global_load_dwordx4 v[52:55], v[56:57], off offset:3072
	v_lshl_add_u64 v[34:35], v[34:35], 0, s[2:3]
	v_lshl_add_u64 v[36:37], v[36:37], 0, s[4:5]
	v_lshl_add_u64 v[106:107], s[82:83], 0, v[34:35]
	global_load_dword v122, v[106:107], off
	v_lshl_add_u64 v[104:105], s[82:83], 0, v[36:37]
	v_add_co_u32_e32 v120, vcc, 0x26980000, v104
	v_add_u32_e32 v32, s0, v32
	s_nop 0
	v_addc_co_u32_e32 v121, vcc, 0, v105, vcc
	global_load_dwordx4 v[104:107], v[120:121], off
	global_load_dwordx4 v[108:111], v[120:121], off offset:1024
	global_load_dwordx4 v[112:115], v[120:121], off offset:2048
	global_load_dwordx4 v[116:119], v[120:121], off offset:3072
	v_lshl_add_u64 v[34:35], v[34:35], 0, s[2:3]
	v_lshl_add_u64 v[36:37], v[36:37], 0, s[4:5]
	s_waitcnt vmcnt(5)
	v_fmamk_f32 v56, v58, 0x3a000000, v33
	v_rsq_f32_e32 v56, v56
	v_lshlrev_b32_e32 v58, 16, v40
	v_and_b32_e32 v59, 0xffff0000, v40
	v_lshlrev_b32_e32 v40, 16, v41
	v_and_b32_e32 v41, 0xffff0000, v41
	v_lshlrev_b32_e32 v60, 16, v42
	v_and_b32_e32 v61, 0xffff0000, v42
	v_lshlrev_b32_e32 v42, 16, v43
	v_and_b32_e32 v43, 0xffff0000, v43
	v_lshlrev_b32_e32 v62, 16, v44
	v_and_b32_e32 v63, 0xffff0000, v44
	v_lshlrev_b32_e32 v44, 16, v45
	v_and_b32_e32 v45, 0xffff0000, v45
	v_lshlrev_b32_e32 v64, 16, v46
	v_and_b32_e32 v65, 0xffff0000, v46
	v_lshlrev_b32_e32 v46, 16, v47
	v_and_b32_e32 v47, 0xffff0000, v47
	v_lshlrev_b32_e32 v66, 16, v48
	v_and_b32_e32 v67, 0xffff0000, v48
	v_lshlrev_b32_e32 v48, 16, v49
	v_and_b32_e32 v49, 0xffff0000, v49
	v_lshlrev_b32_e32 v68, 16, v50
	v_and_b32_e32 v69, 0xffff0000, v50
	v_lshlrev_b32_e32 v50, 16, v51
	v_and_b32_e32 v51, 0xffff0000, v51
	v_lshlrev_b32_e32 v70, 16, v52
	v_and_b32_e32 v71, 0xffff0000, v52
	v_lshlrev_b32_e32 v52, 16, v53
	v_and_b32_e32 v53, 0xffff0000, v53
	v_lshlrev_b32_e32 v72, 16, v54
	v_and_b32_e32 v73, 0xffff0000, v54
	v_lshlrev_b32_e32 v54, 16, v55
	v_and_b32_e32 v55, 0xffff0000, v55
	v_pk_mul_f32 v[58:59], v[56:57], v[58:59] op_sel_hi:[0,1]
	v_pk_mul_f32 v[40:41], v[56:57], v[40:41] op_sel_hi:[0,1]
	v_pk_mul_f32 v[60:61], v[56:57], v[60:61] op_sel_hi:[0,1]
	v_pk_mul_f32 v[74:75], v[56:57], v[42:43] op_sel_hi:[0,1]
	v_pk_mul_f32 v[62:63], v[56:57], v[62:63] op_sel_hi:[0,1]
	v_pk_mul_f32 v[76:77], v[56:57], v[44:45] op_sel_hi:[0,1]
	v_pk_mul_f32 v[64:65], v[56:57], v[64:65] op_sel_hi:[0,1]
	v_pk_mul_f32 v[78:79], v[56:57], v[46:47] op_sel_hi:[0,1]
	v_pk_mul_f32 v[66:67], v[56:57], v[66:67] op_sel_hi:[0,1]
	v_pk_mul_f32 v[80:81], v[56:57], v[48:49] op_sel_hi:[0,1]
	v_pk_mul_f32 v[68:69], v[56:57], v[68:69] op_sel_hi:[0,1]
	v_pk_mul_f32 v[82:83], v[56:57], v[50:51] op_sel_hi:[0,1]
	v_pk_mul_f32 v[70:71], v[56:57], v[70:71] op_sel_hi:[0,1]
	v_pk_mul_f32 v[84:85], v[56:57], v[52:53] op_sel_hi:[0,1]
	v_pk_mul_f32 v[72:73], v[56:57], v[72:73] op_sel_hi:[0,1]
	v_pk_mul_f32 v[86:87], v[56:57], v[54:55] op_sel_hi:[0,1]
	v_pk_mul_f32 v[42:43], v[22:23], v[40:41]
	v_pk_mul_f32 v[40:41], v[20:21], v[58:59]
	v_pk_mul_f32 v[46:47], v[18:19], v[74:75]
	v_pk_mul_f32 v[44:45], v[16:17], v[60:61]
	v_pk_mul_f32 v[50:51], v[6:7], v[76:77]
	v_pk_mul_f32 v[48:49], v[4:5], v[62:63]
	v_pk_mul_f32 v[54:55], v[2:3], v[78:79]
	v_pk_mul_f32 v[52:53], v[0:1], v[64:65]
	v_pk_mul_f32 v[58:59], v[10:11], v[80:81]
	v_pk_mul_f32 v[56:57], v[8:9], v[66:67]
	v_pk_mul_f32 v[62:63], v[14:15], v[82:83]
	v_pk_mul_f32 v[60:61], v[12:13], v[68:69]
	v_pk_mul_f32 v[66:67], v[26:27], v[84:85]
	v_pk_mul_f32 v[64:65], v[24:25], v[70:71]
	v_pk_mul_f32 v[70:71], v[30:31], v[86:87]
	v_pk_mul_f32 v[68:69], v[28:29], v[72:73]
	global_store_dwordx4 v[38:39], v[40:43], off offset:-4096
	global_store_dwordx4 v[38:39], v[44:47], off offset:-4080
	global_store_dwordx4 v[38:39], v[48:51], off offset:-2048
	global_store_dwordx4 v[38:39], v[52:55], off offset:-2032
	global_store_dwordx4 v[38:39], v[56:59], off
	global_store_dwordx4 v[38:39], v[60:63], off offset:16
	global_store_dwordx4 v[38:39], v[64:67], off offset:2048
	global_store_dwordx4 v[38:39], v[68:71], off offset:2064
	v_lshl_add_u64 v[38:39], v[38:39], 0, s[6:7]
; __device__ __forceinline__ float bf_lo(unsigned w) { return __uint_as_float(w << 16); }
; __device__ __forceinline__ float bf_hi(unsigned w) { return __uint_as_float(w & 0xffff0000u); }
; __device__ __forceinline__ float rs_to_r(float ss) { return __builtin_amdgcn_rsqf(ss * (1.0f / DM) + RMS_EPS); }
; __device__ __forceinline__ void final_norm_phase(const bf16_t* __restrict__ hb, const float* __restrict__ g, const float* __restrict__ rs, float* __restrict__ dst, int G, int bid) {
;     ...
;     for (int row = bid * 8 + wave; row < SEQ; row += G * 8) {
;         const bf16_t* p = hb + (size_t)row * DM + lane * 8;
;         u32x4 v[4];
; #pragma unroll
;         for (int i = 0; i < 4; ++i) v[i] = *(const u32x4*)(p + i * 512);
;         const float r = rs_to_r(rs[row]);
;         float* q = dst + (size_t)row * DM + lane * 8;
; #pragma unroll
;         for (int i = 0; i < 4; ++i) {
;             const f32x4 g0 = *(const f32x4*)(g + i * 512 + lane * 8), g1 = *(const f32x4*)(g + i * 512 + lane * 8 + 4);
;             const f32x4 a = (f32x4){bf_lo(v[i].x), bf_hi(v[i].x), bf_lo(v[i].y), bf_hi(v[i].y)}, b = (f32x4){bf_lo(v[i].z), bf_hi(v[i].z), bf_lo(v[i].w), bf_hi(v[i].w)};
;             *(f32x4*)(q + i * 512) = a * r * g0; *(f32x4*)(q + i * 512 + 4) = b * r * g1;
;         }
.Lfn_loop:
	s_nop 1
	v_lshl_add_u64 v[42:43], s[82:83], 0, v[34:35]
	global_load_dword v58, v[42:43], off
	v_lshl_add_u64 v[40:41], s[82:83], 0, v[36:37]
	v_add_co_u32_e32 v56, vcc, 0x26980000, v40
	v_add_u32_e32 v32, s0, v32
	s_nop 0
	v_addc_co_u32_e32 v57, vcc, 0, v41, vcc
	global_load_dwordx4 v[40:43], v[56:57], off
	global_load_dwordx4 v[44:47], v[56:57], off offset:1024
	global_load_dwordx4 v[48:51], v[56:57], off offset:2048
	global_load_dwordx4 v[52:55], v[56:57], off offset:3072
	v_lshl_add_u64 v[34:35], v[34:35], 0, s[2:3]
	v_lshl_add_u64 v[36:37], v[36:37], 0, s[4:5]
	s_waitcnt vmcnt(13)
	v_fmamk_f32 v120, v122, 0x3a000000, v33
	v_rsq_f32_e32 v120, v120
	v_lshlrev_b32_e32 v122, 16, v104
	v_and_b32_e32 v123, 0xffff0000, v104
	v_lshlrev_b32_e32 v104, 16, v105
	v_and_b32_e32 v105, 0xffff0000, v105
	v_lshlrev_b32_e32 v124, 16, v106
	v_and_b32_e32 v125, 0xffff0000, v106
	v_lshlrev_b32_e32 v106, 16, v107
	v_and_b32_e32 v107, 0xffff0000, v107
	v_lshlrev_b32_e32 v126, 16, v108
	v_and_b32_e32 v127, 0xffff0000, v108
	v_lshlrev_b32_e32 v108, 16, v109
	v_and_b32_e32 v109, 0xffff0000, v109
	v_lshlrev_b32_e32 v128, 16, v110
	v_and_b32_e32 v129, 0xffff0000, v110
	v_lshlrev_b32_e32 v110, 16, v111
	v_and_b32_e32 v111, 0xffff0000, v111
	v_lshlrev_b32_e32 v130, 16, v112
	v_and_b32_e32 v131, 0xffff0000, v112
	v_lshlrev_b32_e32 v112, 16, v113
	v_and_b32_e32 v113, 0xffff0000, v113
	v_lshlrev_b32_e32 v132, 16, v114
	v_and_b32_e32 v133, 0xffff0000, v114
	v_lshlrev_b32_e32 v114, 16, v115
	v_and_b32_e32 v115, 0xffff0000, v115
	v_lshlrev_b32_e32 v134, 16, v116
	v_and_b32_e32 v135, 0xffff0000, v116
	v_lshlrev_b32_e32 v116, 16, v117
	v_and_b32_e32 v117, 0xffff0000, v117
	v_lshlrev_b32_e32 v136, 16, v118
	v_and_b32_e32 v137, 0xffff0000, v118
	v_lshlrev_b32_e32 v118, 16, v119
	v_and_b32_e32 v119, 0xffff0000, v119
	v_pk_mul_f32 v[122:123], v[120:121], v[122:123] op_sel_hi:[0,1]
	v_pk_mul_f32 v[104:105], v[120:121], v[104:105] op_sel_hi:[0,1]
	v_pk_mul_f32 v[124:125], v[120:121], v[124:125] op_sel_hi:[0,1]
	v_pk_mul_f32 v[138:139], v[120:121], v[106:107] op_sel_hi:[0,1]
	v_pk_mul_f32 v[126:127], v[120:121], v[126:127] op_sel_hi:[0,1]
	v_pk_mul_f32 v[140:141], v[120:121], v[108:109] op_sel_hi:[0,1]
	v_pk_mul_f32 v[128:129], v[120:121], v[128:129] op_sel_hi:[0,1]
	v_pk_mul_f32 v[142:143], v[120:121], v[110:111] op_sel_hi:[0,1]
	v_pk_mul_f32 v[130:131], v[120:121], v[130:131] op_sel_hi:[0,1]
	v_pk_mul_f32 v[144:145], v[120:121], v[112:113] op_sel_hi:[0,1]
	v_pk_mul_f32 v[132:133], v[120:121], v[132:133] op_sel_hi:[0,1]
	v_pk_mul_f32 v[146:147], v[120:121], v[114:115] op_sel_hi:[0,1]
	v_pk_mul_f32 v[134:135], v[120:121], v[134:135] op_sel_hi:[0,1]
	v_pk_mul_f32 v[148:149], v[120:121], v[116:117] op_sel_hi:[0,1]
	v_pk_mul_f32 v[136:137], v[120:121], v[136:137] op_sel_hi:[0,1]
	v_pk_mul_f32 v[150:151], v[120:121], v[118:119] op_sel_hi:[0,1]
	v_pk_mul_f32 v[106:107], v[22:23], v[104:105]
	v_pk_mul_f32 v[104:105], v[20:21], v[122:123]
	v_pk_mul_f32 v[110:111], v[18:19], v[138:139]
	v_pk_mul_f32 v[108:109], v[16:17], v[124:125]
	v_pk_mul_f32 v[114:115], v[6:7], v[140:141]
	v_pk_mul_f32 v[112:113], v[4:5], v[126:127]
	v_pk_mul_f32 v[118:119], v[2:3], v[142:143]
	v_pk_mul_f32 v[116:117], v[0:1], v[128:129]
	v_pk_mul_f32 v[122:123], v[10:11], v[144:145]
	v_pk_mul_f32 v[120:121], v[8:9], v[130:131]
	v_pk_mul_f32 v[126:127], v[14:15], v[146:147]
	v_pk_mul_f32 v[124:125], v[12:13], v[132:133]
	v_pk_mul_f32 v[130:131], v[26:27], v[148:149]
	v_pk_mul_f32 v[128:129], v[24:25], v[134:135]
	v_pk_mul_f32 v[134:135], v[30:31], v[150:151]
	v_pk_mul_f32 v[132:133], v[28:29], v[136:137]
	global_store_dwordx4 v[38:39], v[104:107], off offset:-4096
	global_store_dwordx4 v[38:39], v[108:111], off offset:-4080
	global_store_dwordx4 v[38:39], v[112:115], off offset:-2048
	global_store_dwordx4 v[38:39], v[116:119], off offset:-2032
	global_store_dwordx4 v[38:39], v[120:123], off
	global_store_dwordx4 v[38:39], v[124:127], off offset:16
	global_store_dwordx4 v[38:39], v[128:131], off offset:2048
	global_store_dwordx4 v[38:39], v[132:135], off offset:2064
	v_lshl_add_u64 v[38:39], v[38:39], 0, s[6:7]
	s_nop 1
	v_lshl_add_u64 v[106:107], s[82:83], 0, v[34:35]
	global_load_dword v122, v[106:107], off
	v_lshl_add_u64 v[104:105], s[82:83], 0, v[36:37]
	v_add_co_u32_e32 v120, vcc, 0x26980000, v104
	v_add_u32_e32 v32, s0, v32
	s_nop 0
	v_addc_co_u32_e32 v121, vcc, 0, v105, vcc
	global_load_dwordx4 v[104:107], v[120:121], off
	global_load_dwordx4 v[108:111], v[120:121], off offset:1024
	global_load_dwordx4 v[112:115], v[120:121], off offset:2048
	global_load_dwordx4 v[116:119], v[120:121], off offset:3072
	v_lshl_add_u64 v[34:35], v[34:35], 0, s[2:3]
	v_lshl_add_u64 v[36:37], v[36:37], 0, s[4:5]
	s_waitcnt vmcnt(13)
; __device__ __forceinline__ float bf_lo(unsigned w) { return __uint_as_float(w << 16); }
; __device__ __forceinline__ float bf_hi(unsigned w) { return __uint_as_float(w & 0xffff0000u); }
; __device__ __forceinline__ float rs_to_r(float ss) { return __builtin_amdgcn_rsqf(ss * (1.0f / DM) + RMS_EPS); }
; __device__ __forceinline__ void final_norm_phase(const bf16_t* __restrict__ hb, const float* __restrict__ g, const float* __restrict__ rs, float* __restrict__ dst, int G, int bid) {
;     ...
;     for (int row = bid * 8 + wave; row < SEQ; row += G * 8) {
;         const bf16_t* p = hb + (size_t)row * DM + lane * 8;
;         u32x4 v[4];
; #pragma unroll
;         for (int i = 0; i < 4; ++i) v[i] = *(const u32x4*)(p + i * 512);
;         const float r = rs_to_r(rs[row]);
;         float* q = dst + (size_t)row * DM + lane * 8;
; #pragma unroll
;         for (int i = 0; i < 4; ++i) {
;             const f32x4 g0 = *(const f32x4*)(g + i * 512 + lane * 8), g1 = *(const f32x4*)(g + i * 512 + lane * 8 + 4);
;             const f32x4 a = (f32x4){bf_lo(v[i].x), bf_hi(v[i].x), bf_lo(v[i].y), bf_hi(v[i].y)}, b = (f32x4){bf_lo(v[i].z), bf_hi(v[i].z), bf_lo(v[i].w), bf_hi(v[i].w)};
;             *(f32x4*)(q + i * 512) = a * r * g0; *(f32x4*)(q + i * 512 + 4) = b * r * g1;
;         }
	v_fmamk_f32 v56, v58, 0x3a000000, v33
	v_rsq_f32_e32 v56, v56
	v_lshlrev_b32_e32 v58, 16, v40
	v_and_b32_e32 v59, 0xffff0000, v40
	v_lshlrev_b32_e32 v40, 16, v41
	v_and_b32_e32 v41, 0xffff0000, v41
	v_lshlrev_b32_e32 v60, 16, v42
	v_and_b32_e32 v61, 0xffff0000, v42
	v_lshlrev_b32_e32 v42, 16, v43
	v_and_b32_e32 v43, 0xffff0000, v43
	v_lshlrev_b32_e32 v62, 16, v44
	v_and_b32_e32 v63, 0xffff0000, v44
	v_lshlrev_b32_e32 v44, 16, v45
	v_and_b32_e32 v45, 0xffff0000, v45
	v_lshlrev_b32_e32 v64, 16, v46
	v_and_b32_e32 v65, 0xffff0000, v46
	v_lshlrev_b32_e32 v46, 16, v47
	v_and_b32_e32 v47, 0xffff0000, v47
	v_lshlrev_b32_e32 v66, 16, v48
	v_and_b32_e32 v67, 0xffff0000, v48
	v_lshlrev_b32_e32 v48, 16, v49
	v_and_b32_e32 v49, 0xffff0000, v49
	v_lshlrev_b32_e32 v68, 16, v50
	v_and_b32_e32 v69, 0xffff0000, v50
	v_lshlrev_b32_e32 v50, 16, v51
	v_and_b32_e32 v51, 0xffff0000, v51
	v_lshlrev_b32_e32 v70, 16, v52
	v_and_b32_e32 v71, 0xffff0000, v52
	v_lshlrev_b32_e32 v52, 16, v53
	v_and_b32_e32 v53, 0xffff0000, v53
	v_lshlrev_b32_e32 v72, 16, v54
	v_and_b32_e32 v73, 0xffff0000, v54
	v_lshlrev_b32_e32 v54, 16, v55
	v_and_b32_e32 v55, 0xffff0000, v55
	v_pk_mul_f32 v[58:59], v[56:57], v[58:59] op_sel_hi:[0,1]
	v_pk_mul_f32 v[40:41], v[56:57], v[40:41] op_sel_hi:[0,1]
	v_pk_mul_f32 v[60:61], v[56:57], v[60:61] op_sel_hi:[0,1]
	v_pk_mul_f32 v[74:75], v[56:57], v[42:43] op_sel_hi:[0,1]
	v_pk_mul_f32 v[62:63], v[56:57], v[62:63] op_sel_hi:[0,1]
	v_pk_mul_f32 v[76:77], v[56:57], v[44:45] op_sel_hi:[0,1]
	v_pk_mul_f32 v[64:65], v[56:57], v[64:65] op_sel_hi:[0,1]
	v_pk_mul_f32 v[78:79], v[56:57], v[46:47] op_sel_hi:[0,1]
	v_pk_mul_f32 v[66:67], v[56:57], v[66:67] op_sel_hi:[0,1]
	v_pk_mul_f32 v[80:81], v[56:57], v[48:49] op_sel_hi:[0,1]
	v_pk_mul_f32 v[68:69], v[56:57], v[68:69] op_sel_hi:[0,1]
	v_pk_mul_f32 v[82:83], v[56:57], v[50:51] op_sel_hi:[0,1]
	v_pk_mul_f32 v[70:71], v[56:57], v[70:71] op_sel_hi:[0,1]
	v_pk_mul_f32 v[84:85], v[56:57], v[52:53] op_sel_hi:[0,1]
	v_pk_mul_f32 v[72:73], v[56:57], v[72:73] op_sel_hi:[0,1]
	v_pk_mul_f32 v[86:87], v[56:57], v[54:55] op_sel_hi:[0,1]
	v_pk_mul_f32 v[42:43], v[22:23], v[40:41]
	v_pk_mul_f32 v[40:41], v[20:21], v[58:59]
	v_pk_mul_f32 v[46:47], v[18:19], v[74:75]
	v_pk_mul_f32 v[44:45], v[16:17], v[60:61]
	v_pk_mul_f32 v[50:51], v[6:7], v[76:77]
	v_pk_mul_f32 v[48:49], v[4:5], v[62:63]
	v_pk_mul_f32 v[54:55], v[2:3], v[78:79]
	v_pk_mul_f32 v[52:53], v[0:1], v[64:65]
	v_pk_mul_f32 v[58:59], v[10:11], v[80:81]
	v_pk_mul_f32 v[56:57], v[8:9], v[66:67]
	v_pk_mul_f32 v[62:63], v[14:15], v[82:83]
	v_pk_mul_f32 v[60:61], v[12:13], v[68:69]
	v_pk_mul_f32 v[66:67], v[26:27], v[84:85]
	v_pk_mul_f32 v[64:65], v[24:25], v[70:71]
	v_pk_mul_f32 v[70:71], v[30:31], v[86:87]
	v_pk_mul_f32 v[68:69], v[28:29], v[72:73]
	global_store_dwordx4 v[38:39], v[40:43], off offset:-4096
	global_store_dwordx4 v[38:39], v[44:47], off offset:-4080
	global_store_dwordx4 v[38:39], v[48:51], off offset:-2048
	global_store_dwordx4 v[38:39], v[52:55], off offset:-2032
	global_store_dwordx4 v[38:39], v[56:59], off
	global_store_dwordx4 v[38:39], v[60:63], off offset:16
	global_store_dwordx4 v[38:39], v[64:67], off offset:2048
	global_store_dwordx4 v[38:39], v[68:71], off offset:2064
	v_lshl_add_u64 v[38:39], v[38:39], 0, s[6:7]
	s_sub_u32 s99, s99, 1
	s_cmp_lg_u32 s99, 0
	s_cbranch_scc1 .Lfn_loop
	s_waitcnt vmcnt(8)
	v_fmamk_f32 v120, v122, 0x3a000000, v33
	v_rsq_f32_e32 v120, v120
	v_lshlrev_b32_e32 v122, 16, v104
	v_and_b32_e32 v123, 0xffff0000, v104
	v_lshlrev_b32_e32 v104, 16, v105
	v_and_b32_e32 v105, 0xffff0000, v105
	v_lshlrev_b32_e32 v124, 16, v106
	v_and_b32_e32 v125, 0xffff0000, v106
	v_lshlrev_b32_e32 v106, 16, v107
	v_and_b32_e32 v107, 0xffff0000, v107
	v_lshlrev_b32_e32 v126, 16, v108
	v_and_b32_e32 v127, 0xffff0000, v108
	v_lshlrev_b32_e32 v108, 16, v109
	v_and_b32_e32 v109, 0xffff0000, v109
	v_lshlrev_b32_e32 v128, 16, v110
	v_and_b32_e32 v129, 0xffff0000, v110
	v_lshlrev_b32_e32 v110, 16, v111
	v_and_b32_e32 v111, 0xffff0000, v111
	v_lshlrev_b32_e32 v130, 16, v112
	v_and_b32_e32 v131, 0xffff0000, v112
	v_lshlrev_b32_e32 v112, 16, v113
	v_and_b32_e32 v113, 0xffff0000, v113
	v_lshlrev_b32_e32 v132, 16, v114
	v_and_b32_e32 v133, 0xffff0000, v114
	v_lshlrev_b32_e32 v114, 16, v115
	v_and_b32_e32 v115, 0xffff0000, v115
	v_lshlrev_b32_e32 v134, 16, v116
	v_and_b32_e32 v135, 0xffff0000, v116
	v_lshlrev_b32_e32 v116, 16, v117
	v_and_b32_e32 v117, 0xffff0000, v117
	v_lshlrev_b32_e32 v136, 16, v118
	v_and_b32_e32 v137, 0xffff0000, v118
	v_lshlrev_b32_e32 v118, 16, v119
	v_and_b32_e32 v119, 0xffff0000, v119
	v_pk_mul_f32 v[122:123], v[120:121], v[122:123] op_sel_hi:[0,1]
	v_pk_mul_f32 v[104:105], v[120:121], v[104:105] op_sel_hi:[0,1]
	v_pk_mul_f32 v[124:125], v[120:121], v[124:125] op_sel_hi:[0,1]
	v_pk_mul_f32 v[138:139], v[120:121], v[106:107] op_sel_hi:[0,1]
	v_pk_mul_f32 v[126:127], v[120:121], v[126:127] op_sel_hi:[0,1]
	v_pk_mul_f32 v[140:141], v[120:121], v[108:109] op_sel_hi:[0,1]
	v_pk_mul_f32 v[128:129], v[120:121], v[128:129] op_sel_hi:[0,1]
	v_pk_mul_f32 v[142:143], v[120:121], v[110:111] op_sel_hi:[0,1]
	v_pk_mul_f32 v[130:131], v[120:121], v[130:131] op_sel_hi:[0,1]
	v_pk_mul_f32 v[144:145], v[120:121], v[112:113] op_sel_hi:[0,1]
	v_pk_mul_f32 v[132:133], v[120:121], v[132:133] op_sel_hi:[0,1]
	v_pk_mul_f32 v[146:147], v[120:121], v[114:115] op_sel_hi:[0,1]
	v_pk_mul_f32 v[134:135], v[120:121], v[134:135] op_sel_hi:[0,1]
	v_pk_mul_f32 v[148:149], v[120:121], v[116:117] op_sel_hi:[0,1]
	v_pk_mul_f32 v[136:137], v[120:121], v[136:137] op_sel_hi:[0,1]
	v_pk_mul_f32 v[150:151], v[120:121], v[118:119] op_sel_hi:[0,1]
	v_pk_mul_f32 v[106:107], v[22:23], v[104:105]
	v_pk_mul_f32 v[104:105], v[20:21], v[122:123]
	v_pk_mul_f32 v[110:111], v[18:19], v[138:139]
	v_pk_mul_f32 v[108:109], v[16:17], v[124:125]
	v_pk_mul_f32 v[114:115], v[6:7], v[140:141]
	v_pk_mul_f32 v[112:113], v[4:5], v[126:127]
	v_pk_mul_f32 v[118:119], v[2:3], v[142:143]
	v_pk_mul_f32 v[116:117], v[0:1], v[128:129]
	v_pk_mul_f32 v[122:123], v[10:11], v[144:145]
	v_pk_mul_f32 v[120:121], v[8:9], v[130:131]
	v_pk_mul_f32 v[126:127], v[14:15], v[146:147]
	v_pk_mul_f32 v[124:125], v[12:13], v[132:133]
	v_pk_mul_f32 v[130:131], v[26:27], v[148:149]
	v_pk_mul_f32 v[128:129], v[24:25], v[134:135]
	v_pk_mul_f32 v[134:135], v[30:31], v[150:151]
	v_pk_mul_f32 v[132:133], v[28:29], v[136:137]
	global_store_dwordx4 v[38:39], v[104:107], off offset:-4096
	global_store_dwordx4 v[38:39], v[108:111], off offset:-4080
	global_store_dwordx4 v[38:39], v[112:115], off offset:-2048
	global_store_dwordx4 v[38:39], v[116:119], off offset:-2032
	global_store_dwordx4 v[38:39], v[120:123], off
	global_store_dwordx4 v[38:39], v[124:127], off offset:16
	global_store_dwordx4 v[38:39], v[128:131], off offset:2048
	global_store_dwordx4 v[38:39], v[132:135], off offset:2064
	v_lshl_add_u64 v[38:39], v[38:39], 0, s[6:7]
	s_branch .LBB0_1639
